# hand-written G_PLE epilogue: residual+pp loads prefetched 3 row-steps deep (was 1), same math order
# speedup vs baseline: 1.0047x; 1.0047x over previous
;     __device__ __forceinline__ void load_row(RowIn& R, size_t off) const {
; #pragma unroll
;         for (int bj = 0; bj < 2; ++bj)
; #pragma unroll
;             for (int n = 0; n < 2; ++n) { const size_t o = off + bj * HALF + n * 16; R.b[bj][n] = *(const f32x4*)(res + o); if (MODE == 1) R.pw[bj][n] = *(const u32x2*)(PP + o); }
;     }
;     __device__ __forceinline__ void operator()(const typename AccT<I8>::type (&acc)[2][2][4][2], const Unit& u, int wr, int wc, int fr, int fq) const {
;         const int row0 = u.pm * BM + wr * 64 + fr, col0 = u.pn * BM + wc * 32 + 4 * fq;
;         f32x4 sv[2][2];
;         if (I8) {
; #pragma unroll
;             for (int bj = 0; bj < 2; ++bj)
; #pragma unroll
;                 for (int n = 0; n < 2; ++n) sv[bj][n] = *(const f32x4*)(swc + col0 + bj * HALF + n * 16);
;         }
;         float rsv[8];
; #pragma unroll
;         for (int s = 0; s < 8; ++s) { const int r = row0 + (s >> 2) * HALF + (s & 3) * 16; float rs = 1.f; if (MODE == 1) rs = __builtin_amdgcn_rsqf(rstd[r] * (1.0f / 4096.0f) + 1e-6f); if (I8) rs *= sxr[r]; rsv[s] = rs; }
;         RowIn cur, nxt;
;         load_row(cur, (size_t)row0 * 4096 + col0);
; #pragma unroll
;         for (int s = 0; s < 8; ++s) { const int ai = s >> 2, m = s & 3; const int r = row0 + ai * HALF + m * 16; const size_t off = (size_t)r * 4096 + col0;
;                 if (s + 1 < 8) load_row(nxt, (size_t)(row0 + ((s + 1) >> 2) * HALF + ((s + 1) & 3) * 16) * 4096 + col0);
.LBB0_2325:
	v_readlane_b32 s54, v254, 14
	v_readlane_b32 s55, v254, 15
	v_lshrrev_b32_e32 v194, 2, v0
	v_and_b32_e32 v194, 64, v194
	v_and_b32_e32 v195, 15, v0
	v_lshl_add_u32 v194, s2, 8, v194
	v_add_u32_e32 v194, v194, v195
	s_lshl_b32 s2, s48, 8
	v_lshrrev_b32_e32 v195, 1, v0
	v_and_b32_e32 v195, 0x60, v195
	v_lshrrev_b32_e32 v255, 2, v0
	v_and_b32_e32 v255, 12, v255
	v_or3_b32 v195, v195, s2, v255
	v_lshlrev_b32_e32 v190, 14, v194
	v_lshl_add_u32 v190, v195, 2, v190
	v_lshrrev_b32_e32 v191, 1, v190
	v_lshlrev_b32_e32 v194, 2, v194
	v_lshlrev_b32_e32 v195, 2, v195
	global_load_dword v242, v194, s[6:7] offset:0
	global_load_dword v243, v194, s[6:7] offset:64
	global_load_dword v244, v194, s[6:7] offset:128
	global_load_dword v245, v194, s[6:7] offset:192
	global_load_dword v246, v194, s[6:7] offset:512
	global_load_dword v247, v194, s[6:7] offset:576
	global_load_dword v248, v194, s[6:7] offset:640
	global_load_dword v249, v194, s[6:7] offset:704
	global_load_dword v250, v194, s[10:11] offset:0
	global_load_dword v251, v194, s[10:11] offset:64
	global_load_dword v252, v194, s[10:11] offset:128
	global_load_dword v253, v194, s[10:11] offset:192
	global_load_dword v182, v194, s[10:11] offset:512
	global_load_dword v188, v194, s[10:11] offset:576
	global_load_dword v192, v194, s[10:11] offset:640
	global_load_dword v196, v194, s[10:11] offset:704
	global_load_dwordx4 v[58:61], v195, s[12:13] offset:0
	global_load_dwordx4 v[66:69], v195, s[12:13] offset:64
	global_load_dwordx4 v[74:77], v195, s[12:13] offset:512
	global_load_dwordx4 v[78:81], v195, s[12:13] offset:576
	global_load_dwordx4 v[146:149], v190, s[54:55] offset:0
	global_load_dwordx4 v[150:153], v190, s[54:55] offset:64
	global_load_dwordx4 v[154:157], v190, s[54:55] offset:512
	global_load_dwordx4 v[158:161], v190, s[54:55] offset:576
	global_load_dwordx2 v[162:163], v191, s[8:9] offset:0
	global_load_dwordx2 v[164:165], v191, s[8:9] offset:32
	global_load_dwordx2 v[178:179], v191, s[8:9] offset:256
	global_load_dwordx2 v[180:181], v191, s[8:9] offset:288
	v_add_u32_e32 v194, 0x40000, v190
	v_add_u32_e32 v195, 0x20000, v191
	global_load_dwordx4 v[198:201], v194, s[54:55] offset:0
	global_load_dwordx4 v[202:205], v194, s[54:55] offset:64
	global_load_dwordx4 v[206:209], v194, s[54:55] offset:512
	global_load_dwordx4 v[210:213], v194, s[54:55] offset:576
	global_load_dwordx2 v[184:185], v195, s[8:9] offset:0
	global_load_dwordx2 v[186:187], v195, s[8:9] offset:32
	global_load_dwordx2 v[214:215], v195, s[8:9] offset:256
	global_load_dwordx2 v[216:217], v195, s[8:9] offset:288
	v_add_u32_e32 v194, 0x80000, v190
	v_add_u32_e32 v195, 0x40000, v191
	global_load_dwordx4 v[218:221], v194, s[54:55] offset:0
	global_load_dwordx4 v[222:225], v194, s[54:55] offset:64
	global_load_dwordx4 v[226:229], v194, s[54:55] offset:512
	global_load_dwordx4 v[230:233], v194, s[54:55] offset:576
	global_load_dwordx2 v[234:235], v195, s[8:9] offset:0
	global_load_dwordx2 v[236:237], v195, s[8:9] offset:32
	global_load_dwordx2 v[238:239], v195, s[8:9] offset:256
	global_load_dwordx2 v[240:241], v195, s[8:9] offset:288
	v_mov_b32_e32 v255, 0xbfb8aa3b
	v_cvt_f32_i32_e32 v142, v142
	v_cvt_f32_i32_e32 v143, v143
	v_cvt_f32_i32_e32 v144, v144
	v_cvt_f32_i32_e32 v145, v145
	v_cvt_f32_i32_e32 v138, v138
	v_cvt_f32_i32_e32 v139, v139
	v_cvt_f32_i32_e32 v140, v140
	v_cvt_f32_i32_e32 v141, v141
	v_cvt_f32_i32_e32 v134, v134
	v_cvt_f32_i32_e32 v135, v135
	v_cvt_f32_i32_e32 v136, v136
	v_cvt_f32_i32_e32 v137, v137
	v_cvt_f32_i32_e32 v130, v130
	v_cvt_f32_i32_e32 v131, v131
	v_cvt_f32_i32_e32 v132, v132
	v_cvt_f32_i32_e32 v133, v133
	v_cvt_f32_i32_e32 v126, v126
	v_cvt_f32_i32_e32 v127, v127
	v_cvt_f32_i32_e32 v128, v128
	v_cvt_f32_i32_e32 v129, v129
	v_cvt_f32_i32_e32 v122, v122
	v_cvt_f32_i32_e32 v123, v123
	v_cvt_f32_i32_e32 v124, v124
	v_cvt_f32_i32_e32 v125, v125
	v_cvt_f32_i32_e32 v118, v118
	v_cvt_f32_i32_e32 v119, v119
	v_cvt_f32_i32_e32 v120, v120
	v_cvt_f32_i32_e32 v121, v121
	v_cvt_f32_i32_e32 v114, v114
	v_cvt_f32_i32_e32 v115, v115
	v_cvt_f32_i32_e32 v116, v116
	v_cvt_f32_i32_e32 v117, v117
	v_cvt_f32_i32_e32 v110, v110
	v_cvt_f32_i32_e32 v111, v111
	v_cvt_f32_i32_e32 v112, v112
	v_cvt_f32_i32_e32 v113, v113
	v_cvt_f32_i32_e32 v106, v106
	v_cvt_f32_i32_e32 v107, v107
	v_cvt_f32_i32_e32 v108, v108
	v_cvt_f32_i32_e32 v109, v109
	v_cvt_f32_i32_e32 v102, v102
	v_cvt_f32_i32_e32 v103, v103
	v_cvt_f32_i32_e32 v104, v104
	v_cvt_f32_i32_e32 v105, v105
	v_cvt_f32_i32_e32 v98, v98
	v_cvt_f32_i32_e32 v99, v99
	v_cvt_f32_i32_e32 v100, v100
	v_cvt_f32_i32_e32 v101, v101
	v_cvt_f32_i32_e32 v94, v94
	v_cvt_f32_i32_e32 v95, v95
	v_cvt_f32_i32_e32 v96, v96
	v_cvt_f32_i32_e32 v97, v97
	v_cvt_f32_i32_e32 v90, v90
	v_cvt_f32_i32_e32 v91, v91
	v_cvt_f32_i32_e32 v92, v92
	v_cvt_f32_i32_e32 v93, v93
	v_cvt_f32_i32_e32 v86, v86
	v_cvt_f32_i32_e32 v87, v87
	v_cvt_f32_i32_e32 v88, v88
	v_cvt_f32_i32_e32 v89, v89
	v_cvt_f32_i32_e32 v82, v82
	v_cvt_f32_i32_e32 v83, v83
	v_cvt_f32_i32_e32 v84, v84
	v_cvt_f32_i32_e32 v85, v85
	v_cvt_f32_i32_e32 v70, v70
	v_cvt_f32_i32_e32 v71, v71
	v_cvt_f32_i32_e32 v72, v72
	v_cvt_f32_i32_e32 v73, v73
	v_cvt_f32_i32_e32 v62, v62
	v_cvt_f32_i32_e32 v63, v63
	v_cvt_f32_i32_e32 v64, v64
	v_cvt_f32_i32_e32 v65, v65
	v_cvt_f32_i32_e32 v54, v54
	v_cvt_f32_i32_e32 v55, v55
	v_cvt_f32_i32_e32 v56, v56
	v_cvt_f32_i32_e32 v57, v57
	v_cvt_f32_i32_e32 v50, v50
	v_cvt_f32_i32_e32 v51, v51
	v_cvt_f32_i32_e32 v52, v52
	v_cvt_f32_i32_e32 v53, v53
	v_cvt_f32_i32_e32 v46, v46
	v_cvt_f32_i32_e32 v47, v47
	v_cvt_f32_i32_e32 v48, v48
	v_cvt_f32_i32_e32 v49, v49
	v_cvt_f32_i32_e32 v42, v42
	v_cvt_f32_i32_e32 v43, v43
	v_cvt_f32_i32_e32 v44, v44
	v_cvt_f32_i32_e32 v45, v45
	v_cvt_f32_i32_e32 v38, v38
	v_cvt_f32_i32_e32 v39, v39
	v_cvt_f32_i32_e32 v40, v40
	v_cvt_f32_i32_e32 v41, v41
	v_cvt_f32_i32_e32 v34, v34
	v_cvt_f32_i32_e32 v35, v35
	v_cvt_f32_i32_e32 v36, v36
	v_cvt_f32_i32_e32 v37, v37
	v_cvt_f32_i32_e32 v30, v30
	v_cvt_f32_i32_e32 v31, v31
	v_cvt_f32_i32_e32 v32, v32
	v_cvt_f32_i32_e32 v33, v33
	v_cvt_f32_i32_e32 v26, v26
	v_cvt_f32_i32_e32 v27, v27
	v_cvt_f32_i32_e32 v28, v28
	v_cvt_f32_i32_e32 v29, v29
	v_cvt_f32_i32_e32 v22, v22
	v_cvt_f32_i32_e32 v23, v23
	v_cvt_f32_i32_e32 v24, v24
	v_cvt_f32_i32_e32 v25, v25
	v_cvt_f32_i32_e32 v18, v18
	v_cvt_f32_i32_e32 v19, v19
	v_cvt_f32_i32_e32 v20, v20
	v_cvt_f32_i32_e32 v21, v21
	v_cvt_f32_i32_e32 v14, v14
	v_cvt_f32_i32_e32 v15, v15
	v_cvt_f32_i32_e32 v16, v16
	v_cvt_f32_i32_e32 v17, v17
	v_cvt_f32_i32_e32 v10, v10
	v_cvt_f32_i32_e32 v11, v11
	v_cvt_f32_i32_e32 v12, v12
	v_cvt_f32_i32_e32 v13, v13
	v_cvt_f32_i32_e32 v6, v6
	v_cvt_f32_i32_e32 v7, v7
	v_cvt_f32_i32_e32 v8, v8
	v_cvt_f32_i32_e32 v9, v9
	v_cvt_f32_i32_e32 v2, v2
	v_cvt_f32_i32_e32 v3, v3
	v_cvt_f32_i32_e32 v4, v4
	v_cvt_f32_i32_e32 v5, v5
	s_waitcnt vmcnt(28)
; __device__ __forceinline__ unsigned cvt_pk_bf16(float lo, float hi) { unsigned r; asm volatile("s_nop 0\n\tv_cvt_pk_bf16_f32 %0, %1, %2" : "=v"(r) : "v"(lo), "v"(hi)); return r; }
;     __device__ __forceinline__ void operator()(const typename AccT<I8>::type (&acc)[2][2][4][2], const Unit& u, int wr, int wc, int fr, int fq) const {
;     ...
;         for (int s = 0; s < 8; ++s) { const int r = row0 + (s >> 2) * HALF + (s & 3) * 16; float rs = 1.f; if (MODE == 1) rs = __builtin_amdgcn_rsqf(rstd[r] * (1.0f / 4096.0f) + 1e-6f); if (I8) rs *= sxr[r]; rsv[s] = rs; }
;         RowIn cur, nxt;
;         load_row(cur, (size_t)row0 * 4096 + col0);
; #pragma unroll
;         for (int s = 0; s < 8; ++s) { const int ai = s >> 2, m = s & 3; const int r = row0 + ai * HALF + m * 16; const size_t off = (size_t)r * 4096 + col0;
;                 if (s + 1 < 8) load_row(nxt, (size_t)(row0 + ((s + 1) >> 2) * HALF + ((s + 1) & 3) * 16) * 4096 + col0);
;                 const float rs = rsv[s];
;                 float ss = 0.f, mx = 0.f;
; #pragma unroll
;                 for (int bj = 0; bj < 2; ++bj)
; #pragma unroll
;                     for (int n = 0; n < 2; ++n) { const size_t o = off + bj * HALF + n * 16; const f32x4 b = cur.b[bj][n]; f32x4 v;
;                         if constexpr (I8) v = __builtin_convertvector(acc[ai][bj][m][n], f32x4) * rs * sv[bj][n]; else v = acc[ai][bj][m][n];
;                         if (MODE == 1) { const u32x2 pw = cur.pw[bj][n]; const f32x4 pp = (f32x4){bf_lo(pw.x), bf_hi(pw.x), bf_lo(pw.y), bf_hi(pw.y)}; v = sig4(I8 ? v : v * rs) * pp; }
;                         const f32x4 x = b + v; *(f32x4*)(out + o) = x;
;                         if (MODE == 0 && XB) { u32x2 w; w.x = cvt_pk_bf16(x[0], x[1]); w.y = cvt_pk_bf16(x[2], x[3]); *(u32x2*)(XB + o) = w; ss += (x[0] * x[0] + x[1] * x[1]) + (x[2] * x[2] + x[3] * x[3]);
;                             if (RM) mx = fmaxf(fmaxf(mx, fmaxf(fabsf(x[0]), fabsf(x[1]))), fmaxf(fabsf(x[2]), fabsf(x[3]))); } }
;                 if (MODE == 0 && XB) { ss += __shfl_xor(ss, 16); ss += __shfl_xor(ss, 32); if (fq == 0) unsafeAtomicAdd(SS + r, ss);
;                     if (RM) { mx = fmaxf(mx, __shfl_xor(mx, 16)); mx = fmaxf(mx, __shfl_xor(mx, 32)); if (fq == 0) atomicMax(RM + r, __builtin_bit_cast(unsigned, mx)); } }
;                 cur = nxt; }
	v_fmamk_f32 v242, v242, 0x39800000, v197
	v_fmamk_f32 v243, v243, 0x39800000, v197
	v_fmamk_f32 v244, v244, 0x39800000, v197
	v_fmamk_f32 v245, v245, 0x39800000, v197
	v_fmamk_f32 v246, v246, 0x39800000, v197
	v_fmamk_f32 v247, v247, 0x39800000, v197
	v_fmamk_f32 v248, v248, 0x39800000, v197
	v_fmamk_f32 v249, v249, 0x39800000, v197
	v_rsq_f32_e32 v242, v242
	v_rsq_f32_e32 v243, v243
	v_rsq_f32_e32 v244, v244
	v_rsq_f32_e32 v245, v245
	v_rsq_f32_e32 v246, v246
	v_rsq_f32_e32 v247, v247
	v_rsq_f32_e32 v248, v248
	v_rsq_f32_e32 v249, v249
	v_mul_f32_e32 v242, v250, v242
	v_mul_f32_e32 v243, v251, v243
	v_mul_f32_e32 v244, v252, v244
	v_mul_f32_e32 v245, v253, v245
	v_mul_f32_e32 v246, v182, v246
	v_mul_f32_e32 v247, v188, v247
	v_mul_f32_e32 v248, v192, v248
	v_mul_f32_e32 v249, v196, v249
	s_waitcnt vmcnt(24)
	v_pk_mul_f32 v[142:143], v[242:243], v[142:143] op_sel:[0,0] op_sel_hi:[0,1]
	v_pk_mul_f32 v[144:145], v[242:243], v[144:145] op_sel:[0,0] op_sel_hi:[0,1]
	v_pk_mul_f32 v[142:143], v[58:59], v[142:143]
	v_pk_mul_f32 v[144:145], v[60:61], v[144:145]
	v_mul_f32_e32 v142, v255, v142
	v_mul_f32_e32 v143, v255, v143
	v_mul_f32_e32 v144, v255, v144
	v_mul_f32_e32 v145, v255, v145
	v_exp_f32_e32 v142, v142
	v_exp_f32_e32 v143, v143
	v_exp_f32_e32 v144, v144
	v_exp_f32_e32 v145, v145
	v_add_f32_e32 v142, 1.0, v142
	v_add_f32_e32 v143, 1.0, v143
	v_add_f32_e32 v144, 1.0, v144
	v_add_f32_e32 v145, 1.0, v145
	v_rcp_f32_e32 v142, v142
	v_rcp_f32_e32 v143, v143
	v_rcp_f32_e32 v144, v144
	v_rcp_f32_e32 v145, v145
	s_waitcnt vmcnt(19)
	v_lshlrev_b32_e32 v250, 16, v162
	v_and_b32_e32 v251, 0xffff0000, v162
	v_lshlrev_b32_e32 v252, 16, v163
	v_and_b32_e32 v253, 0xffff0000, v163
	v_pk_fma_f32 v[146:147], v[142:143], v[250:251], v[146:147]
	v_pk_fma_f32 v[148:149], v[144:145], v[252:253], v[148:149]
	global_store_dwordx4 v190, v[146:149], s[54:55] offset:0
	v_pk_mul_f32 v[138:139], v[242:243], v[138:139] op_sel:[0,0] op_sel_hi:[0,1]
	v_pk_mul_f32 v[140:141], v[242:243], v[140:141] op_sel:[0,0] op_sel_hi:[0,1]
	v_pk_mul_f32 v[138:139], v[66:67], v[138:139]
	v_pk_mul_f32 v[140:141], v[68:69], v[140:141]
	v_mul_f32_e32 v138, v255, v138
	v_mul_f32_e32 v139, v255, v139
	v_mul_f32_e32 v140, v255, v140
	v_mul_f32_e32 v141, v255, v141
	v_exp_f32_e32 v138, v138
	v_exp_f32_e32 v139, v139
	v_exp_f32_e32 v140, v140
	v_exp_f32_e32 v141, v141
	v_add_f32_e32 v138, 1.0, v138
	v_add_f32_e32 v139, 1.0, v139
	v_add_f32_e32 v140, 1.0, v140
	v_add_f32_e32 v141, 1.0, v141
	v_rcp_f32_e32 v138, v138
	v_rcp_f32_e32 v139, v139
	v_rcp_f32_e32 v140, v140
	v_rcp_f32_e32 v141, v141
	s_waitcnt vmcnt(19)
	v_lshlrev_b32_e32 v250, 16, v164
	v_and_b32_e32 v251, 0xffff0000, v164
	v_lshlrev_b32_e32 v252, 16, v165
	v_and_b32_e32 v253, 0xffff0000, v165
	v_pk_fma_f32 v[150:151], v[138:139], v[250:251], v[150:151]
	v_pk_fma_f32 v[152:153], v[140:141], v[252:253], v[152:153]
	global_store_dwordx4 v190, v[150:153], s[54:55] offset:64
	v_pk_mul_f32 v[134:135], v[242:243], v[134:135] op_sel:[0,0] op_sel_hi:[0,1]
	v_pk_mul_f32 v[136:137], v[242:243], v[136:137] op_sel:[0,0] op_sel_hi:[0,1]
	v_pk_mul_f32 v[134:135], v[74:75], v[134:135]
	v_pk_mul_f32 v[136:137], v[76:77], v[136:137]
	v_mul_f32_e32 v134, v255, v134
	v_mul_f32_e32 v135, v255, v135
	v_mul_f32_e32 v136, v255, v136
	v_mul_f32_e32 v137, v255, v137
	v_exp_f32_e32 v134, v134
	v_exp_f32_e32 v135, v135
	v_exp_f32_e32 v136, v136
	v_exp_f32_e32 v137, v137
	v_add_f32_e32 v134, 1.0, v134
	v_add_f32_e32 v135, 1.0, v135
	v_add_f32_e32 v136, 1.0, v136
	v_add_f32_e32 v137, 1.0, v137
	v_rcp_f32_e32 v134, v134
	v_rcp_f32_e32 v135, v135
	v_rcp_f32_e32 v136, v136
	v_rcp_f32_e32 v137, v137
	s_waitcnt vmcnt(19)
	v_lshlrev_b32_e32 v250, 16, v178
	v_and_b32_e32 v251, 0xffff0000, v178
	v_lshlrev_b32_e32 v252, 16, v179
	v_and_b32_e32 v253, 0xffff0000, v179
	v_pk_fma_f32 v[154:155], v[134:135], v[250:251], v[154:155]
	v_pk_fma_f32 v[156:157], v[136:137], v[252:253], v[156:157]
	global_store_dwordx4 v190, v[154:157], s[54:55] offset:512
	v_pk_mul_f32 v[130:131], v[242:243], v[130:131] op_sel:[0,0] op_sel_hi:[0,1]
	v_pk_mul_f32 v[132:133], v[242:243], v[132:133] op_sel:[0,0] op_sel_hi:[0,1]
	v_pk_mul_f32 v[130:131], v[78:79], v[130:131]
	v_pk_mul_f32 v[132:133], v[80:81], v[132:133]
	v_mul_f32_e32 v130, v255, v130
	v_mul_f32_e32 v131, v255, v131
	v_mul_f32_e32 v132, v255, v132
	v_mul_f32_e32 v133, v255, v133
	v_exp_f32_e32 v130, v130
	v_exp_f32_e32 v131, v131
	v_exp_f32_e32 v132, v132
	v_exp_f32_e32 v133, v133
	v_add_f32_e32 v130, 1.0, v130
	v_add_f32_e32 v131, 1.0, v131
	v_add_f32_e32 v132, 1.0, v132
	v_add_f32_e32 v133, 1.0, v133
	v_rcp_f32_e32 v130, v130
	v_rcp_f32_e32 v131, v131
	v_rcp_f32_e32 v132, v132
	v_rcp_f32_e32 v133, v133
	s_waitcnt vmcnt(19)
	v_lshlrev_b32_e32 v250, 16, v180
	v_and_b32_e32 v251, 0xffff0000, v180
	v_lshlrev_b32_e32 v252, 16, v181
	v_and_b32_e32 v253, 0xffff0000, v181
	v_pk_fma_f32 v[158:159], v[130:131], v[250:251], v[158:159]
	v_pk_fma_f32 v[160:161], v[132:133], v[252:253], v[160:161]
	global_store_dwordx4 v190, v[158:161], s[54:55] offset:576
	v_add_u32_e32 v194, 0xc0000, v190
	v_add_u32_e32 v195, 0x60000, v191
	global_load_dwordx4 v[146:149], v194, s[54:55] offset:0
	global_load_dwordx4 v[150:153], v194, s[54:55] offset:64
	global_load_dwordx4 v[154:157], v194, s[54:55] offset:512
	global_load_dwordx4 v[158:161], v194, s[54:55] offset:576
	global_load_dwordx2 v[162:163], v195, s[8:9] offset:0
	global_load_dwordx2 v[164:165], v195, s[8:9] offset:32
	global_load_dwordx2 v[178:179], v195, s[8:9] offset:256
	global_load_dwordx2 v[180:181], v195, s[8:9] offset:288
	v_add_u32_e32 v194, 0x40000, v190
	v_pk_mul_f32 v[126:127], v[242:243], v[126:127] op_sel:[1,0] op_sel_hi:[1,1]
	v_pk_mul_f32 v[128:129], v[242:243], v[128:129] op_sel:[1,0] op_sel_hi:[1,1]
	v_pk_mul_f32 v[126:127], v[58:59], v[126:127]
	v_pk_mul_f32 v[128:129], v[60:61], v[128:129]
	v_mul_f32_e32 v126, v255, v126
	v_mul_f32_e32 v127, v255, v127
	v_mul_f32_e32 v128, v255, v128
	v_mul_f32_e32 v129, v255, v129
	v_exp_f32_e32 v126, v126
	v_exp_f32_e32 v127, v127
	v_exp_f32_e32 v128, v128
	v_exp_f32_e32 v129, v129
	v_add_f32_e32 v126, 1.0, v126
	v_add_f32_e32 v127, 1.0, v127
	v_add_f32_e32 v128, 1.0, v128
	v_add_f32_e32 v129, 1.0, v129
	v_rcp_f32_e32 v126, v126
	v_rcp_f32_e32 v127, v127
	v_rcp_f32_e32 v128, v128
	v_rcp_f32_e32 v129, v129
	s_waitcnt vmcnt(23)
; __device__ __forceinline__ unsigned cvt_pk_bf16(float lo, float hi) { unsigned r; asm volatile("s_nop 0\n\tv_cvt_pk_bf16_f32 %0, %1, %2" : "=v"(r) : "v"(lo), "v"(hi)); return r; }
; __device__ __forceinline__ f32x4 sig4(const f32x4 v) { return (f32x4){sigmoidf_(v[0]), sigmoidf_(v[1]), sigmoidf_(v[2]), sigmoidf_(v[3])}; }
;     __device__ __forceinline__ void operator()(const typename AccT<I8>::type (&acc)[2][2][4][2], const Unit& u, int wr, int wc, int fr, int fq) const {
;     ...
;         for (int s = 0; s < 8; ++s) { const int ai = s >> 2, m = s & 3; const int r = row0 + ai * HALF + m * 16; const size_t off = (size_t)r * 4096 + col0;
;                 if (s + 1 < 8) load_row(nxt, (size_t)(row0 + ((s + 1) >> 2) * HALF + ((s + 1) & 3) * 16) * 4096 + col0);
;                 const float rs = rsv[s];
;                 float ss = 0.f, mx = 0.f;
; #pragma unroll
;                 for (int bj = 0; bj < 2; ++bj)
; #pragma unroll
;                     for (int n = 0; n < 2; ++n) { const size_t o = off + bj * HALF + n * 16; const f32x4 b = cur.b[bj][n]; f32x4 v;
;                         if constexpr (I8) v = __builtin_convertvector(acc[ai][bj][m][n], f32x4) * rs * sv[bj][n]; else v = acc[ai][bj][m][n];
;                         if (MODE == 1) { const u32x2 pw = cur.pw[bj][n]; const f32x4 pp = (f32x4){bf_lo(pw.x), bf_hi(pw.x), bf_lo(pw.y), bf_hi(pw.y)}; v = sig4(I8 ? v : v * rs) * pp; }
;                         const f32x4 x = b + v; *(f32x4*)(out + o) = x;
;                         if (MODE == 0 && XB) { u32x2 w; w.x = cvt_pk_bf16(x[0], x[1]); w.y = cvt_pk_bf16(x[2], x[3]); *(u32x2*)(XB + o) = w; ss += (x[0] * x[0] + x[1] * x[1]) + (x[2] * x[2] + x[3] * x[3]);
;                             if (RM) mx = fmaxf(fmaxf(mx, fmaxf(fabsf(x[0]), fabsf(x[1]))), fmaxf(fabsf(x[2]), fabsf(x[3]))); } }
;                 if (MODE == 0 && XB) { ss += __shfl_xor(ss, 16); ss += __shfl_xor(ss, 32); if (fq == 0) unsafeAtomicAdd(SS + r, ss);
;                     if (RM) { mx = fmaxf(mx, __shfl_xor(mx, 16)); mx = fmaxf(mx, __shfl_xor(mx, 32)); if (fq == 0) atomicMax(RM + r, __builtin_bit_cast(unsigned, mx)); } }
;                 cur = nxt; }
	v_lshlrev_b32_e32 v250, 16, v184
	v_and_b32_e32 v251, 0xffff0000, v184
	v_lshlrev_b32_e32 v252, 16, v185
	v_and_b32_e32 v253, 0xffff0000, v185
	v_pk_fma_f32 v[198:199], v[126:127], v[250:251], v[198:199]
	v_pk_fma_f32 v[200:201], v[128:129], v[252:253], v[200:201]
	global_store_dwordx4 v194, v[198:201], s[54:55] offset:0
	v_pk_mul_f32 v[122:123], v[242:243], v[122:123] op_sel:[1,0] op_sel_hi:[1,1]
	v_pk_mul_f32 v[124:125], v[242:243], v[124:125] op_sel:[1,0] op_sel_hi:[1,1]
	v_pk_mul_f32 v[122:123], v[66:67], v[122:123]
	v_pk_mul_f32 v[124:125], v[68:69], v[124:125]
	v_mul_f32_e32 v122, v255, v122
	v_mul_f32_e32 v123, v255, v123
	v_mul_f32_e32 v124, v255, v124
	v_mul_f32_e32 v125, v255, v125
	v_exp_f32_e32 v122, v122
	v_exp_f32_e32 v123, v123
	v_exp_f32_e32 v124, v124
	v_exp_f32_e32 v125, v125
	v_add_f32_e32 v122, 1.0, v122
	v_add_f32_e32 v123, 1.0, v123
	v_add_f32_e32 v124, 1.0, v124
	v_add_f32_e32 v125, 1.0, v125
	v_rcp_f32_e32 v122, v122
	v_rcp_f32_e32 v123, v123
	v_rcp_f32_e32 v124, v124
	v_rcp_f32_e32 v125, v125
	s_waitcnt vmcnt(23)
	v_lshlrev_b32_e32 v250, 16, v186
	v_and_b32_e32 v251, 0xffff0000, v186
	v_lshlrev_b32_e32 v252, 16, v187
	v_and_b32_e32 v253, 0xffff0000, v187
	v_pk_fma_f32 v[202:203], v[122:123], v[250:251], v[202:203]
	v_pk_fma_f32 v[204:205], v[124:125], v[252:253], v[204:205]
	global_store_dwordx4 v194, v[202:205], s[54:55] offset:64
	v_pk_mul_f32 v[118:119], v[242:243], v[118:119] op_sel:[1,0] op_sel_hi:[1,1]
	v_pk_mul_f32 v[120:121], v[242:243], v[120:121] op_sel:[1,0] op_sel_hi:[1,1]
	v_pk_mul_f32 v[118:119], v[74:75], v[118:119]
	v_pk_mul_f32 v[120:121], v[76:77], v[120:121]
	v_mul_f32_e32 v118, v255, v118
	v_mul_f32_e32 v119, v255, v119
	v_mul_f32_e32 v120, v255, v120
	v_mul_f32_e32 v121, v255, v121
	v_exp_f32_e32 v118, v118
	v_exp_f32_e32 v119, v119
	v_exp_f32_e32 v120, v120
	v_exp_f32_e32 v121, v121
	v_add_f32_e32 v118, 1.0, v118
	v_add_f32_e32 v119, 1.0, v119
	v_add_f32_e32 v120, 1.0, v120
	v_add_f32_e32 v121, 1.0, v121
	v_rcp_f32_e32 v118, v118
	v_rcp_f32_e32 v119, v119
	v_rcp_f32_e32 v120, v120
	v_rcp_f32_e32 v121, v121
	s_waitcnt vmcnt(23)
	v_lshlrev_b32_e32 v250, 16, v214
	v_and_b32_e32 v251, 0xffff0000, v214
	v_lshlrev_b32_e32 v252, 16, v215
	v_and_b32_e32 v253, 0xffff0000, v215
	v_pk_fma_f32 v[206:207], v[118:119], v[250:251], v[206:207]
	v_pk_fma_f32 v[208:209], v[120:121], v[252:253], v[208:209]
	global_store_dwordx4 v194, v[206:209], s[54:55] offset:512
	v_pk_mul_f32 v[114:115], v[242:243], v[114:115] op_sel:[1,0] op_sel_hi:[1,1]
	v_pk_mul_f32 v[116:117], v[242:243], v[116:117] op_sel:[1,0] op_sel_hi:[1,1]
	v_pk_mul_f32 v[114:115], v[78:79], v[114:115]
	v_pk_mul_f32 v[116:117], v[80:81], v[116:117]
	v_mul_f32_e32 v114, v255, v114
	v_mul_f32_e32 v115, v255, v115
	v_mul_f32_e32 v116, v255, v116
	v_mul_f32_e32 v117, v255, v117
	v_exp_f32_e32 v114, v114
	v_exp_f32_e32 v115, v115
	v_exp_f32_e32 v116, v116
	v_exp_f32_e32 v117, v117
	v_add_f32_e32 v114, 1.0, v114
	v_add_f32_e32 v115, 1.0, v115
	v_add_f32_e32 v116, 1.0, v116
	v_add_f32_e32 v117, 1.0, v117
	v_rcp_f32_e32 v114, v114
	v_rcp_f32_e32 v115, v115
	v_rcp_f32_e32 v116, v116
	v_rcp_f32_e32 v117, v117
	s_waitcnt vmcnt(23)
	v_lshlrev_b32_e32 v250, 16, v216
	v_and_b32_e32 v251, 0xffff0000, v216
	v_lshlrev_b32_e32 v252, 16, v217
	v_and_b32_e32 v253, 0xffff0000, v217
	v_pk_fma_f32 v[210:211], v[114:115], v[250:251], v[210:211]
	v_pk_fma_f32 v[212:213], v[116:117], v[252:253], v[212:213]
	global_store_dwordx4 v194, v[210:213], s[54:55] offset:576
	v_add_u32_e32 v194, 0x200000, v190
	v_add_u32_e32 v195, 0x100000, v191
	global_load_dwordx4 v[198:201], v194, s[54:55] offset:0
	global_load_dwordx4 v[202:205], v194, s[54:55] offset:64
	global_load_dwordx4 v[206:209], v194, s[54:55] offset:512
	global_load_dwordx4 v[210:213], v194, s[54:55] offset:576
	global_load_dwordx2 v[184:185], v195, s[8:9] offset:0
	global_load_dwordx2 v[186:187], v195, s[8:9] offset:32
	global_load_dwordx2 v[214:215], v195, s[8:9] offset:256
	global_load_dwordx2 v[216:217], v195, s[8:9] offset:288
	v_add_u32_e32 v194, 0x240000, v190
	v_add_u32_e32 v195, 0x120000, v191
	global_load_dwordx4 v[142:145], v194, s[54:55] offset:0
	global_load_dwordx4 v[138:141], v194, s[54:55] offset:64
	global_load_dwordx4 v[134:137], v194, s[54:55] offset:512
	global_load_dwordx4 v[130:133], v194, s[54:55] offset:576
	global_load_dwordx2 v[126:127], v195, s[8:9] offset:0
	global_load_dwordx2 v[128:129], v195, s[8:9] offset:32
	global_load_dwordx2 v[122:123], v195, s[8:9] offset:256
	global_load_dwordx2 v[124:125], v195, s[8:9] offset:288
	v_add_u32_e32 v194, 0x80000, v190
	v_pk_mul_f32 v[110:111], v[244:245], v[110:111] op_sel:[0,0] op_sel_hi:[0,1]
	v_pk_mul_f32 v[112:113], v[244:245], v[112:113] op_sel:[0,0] op_sel_hi:[0,1]
	v_pk_mul_f32 v[110:111], v[58:59], v[110:111]
	v_pk_mul_f32 v[112:113], v[60:61], v[112:113]
	v_mul_f32_e32 v110, v255, v110
	v_mul_f32_e32 v111, v255, v111
	v_mul_f32_e32 v112, v255, v112
	v_mul_f32_e32 v113, v255, v113
	v_exp_f32_e32 v110, v110
	v_exp_f32_e32 v111, v111
	v_exp_f32_e32 v112, v112
	v_exp_f32_e32 v113, v113
	v_add_f32_e32 v110, 1.0, v110
	v_add_f32_e32 v111, 1.0, v111
	v_add_f32_e32 v112, 1.0, v112
	v_add_f32_e32 v113, 1.0, v113
	v_rcp_f32_e32 v110, v110
	v_rcp_f32_e32 v111, v111
	v_rcp_f32_e32 v112, v112
	v_rcp_f32_e32 v113, v113
	s_waitcnt vmcnt(35)
; __device__ __forceinline__ unsigned cvt_pk_bf16(float lo, float hi) { unsigned r; asm volatile("s_nop 0\n\tv_cvt_pk_bf16_f32 %0, %1, %2" : "=v"(r) : "v"(lo), "v"(hi)); return r; }
; __device__ __forceinline__ f32x4 sig4(const f32x4 v) { return (f32x4){sigmoidf_(v[0]), sigmoidf_(v[1]), sigmoidf_(v[2]), sigmoidf_(v[3])}; }
;     __device__ __forceinline__ void operator()(const typename AccT<I8>::type (&acc)[2][2][4][2], const Unit& u, int wr, int wc, int fr, int fq) const {
;     ...
;         for (int s = 0; s < 8; ++s) { const int ai = s >> 2, m = s & 3; const int r = row0 + ai * HALF + m * 16; const size_t off = (size_t)r * 4096 + col0;
;                 if (s + 1 < 8) load_row(nxt, (size_t)(row0 + ((s + 1) >> 2) * HALF + ((s + 1) & 3) * 16) * 4096 + col0);
;                 const float rs = rsv[s];
;                 float ss = 0.f, mx = 0.f;
; #pragma unroll
;                 for (int bj = 0; bj < 2; ++bj)
; #pragma unroll
;                     for (int n = 0; n < 2; ++n) { const size_t o = off + bj * HALF + n * 16; const f32x4 b = cur.b[bj][n]; f32x4 v;
;                         if constexpr (I8) v = __builtin_convertvector(acc[ai][bj][m][n], f32x4) * rs * sv[bj][n]; else v = acc[ai][bj][m][n];
;                         if (MODE == 1) { const u32x2 pw = cur.pw[bj][n]; const f32x4 pp = (f32x4){bf_lo(pw.x), bf_hi(pw.x), bf_lo(pw.y), bf_hi(pw.y)}; v = sig4(I8 ? v : v * rs) * pp; }
;                         const f32x4 x = b + v; *(f32x4*)(out + o) = x;
;                         if (MODE == 0 && XB) { u32x2 w; w.x = cvt_pk_bf16(x[0], x[1]); w.y = cvt_pk_bf16(x[2], x[3]); *(u32x2*)(XB + o) = w; ss += (x[0] * x[0] + x[1] * x[1]) + (x[2] * x[2] + x[3] * x[3]);
;                             if (RM) mx = fmaxf(fmaxf(mx, fmaxf(fabsf(x[0]), fabsf(x[1]))), fmaxf(fabsf(x[2]), fabsf(x[3]))); } }
;                 if (MODE == 0 && XB) { ss += __shfl_xor(ss, 16); ss += __shfl_xor(ss, 32); if (fq == 0) unsafeAtomicAdd(SS + r, ss);
;                     if (RM) { mx = fmaxf(mx, __shfl_xor(mx, 16)); mx = fmaxf(mx, __shfl_xor(mx, 32)); if (fq == 0) atomicMax(RM + r, __builtin_bit_cast(unsigned, mx)); } }
;                 cur = nxt; }
	v_lshlrev_b32_e32 v250, 16, v234
	v_and_b32_e32 v251, 0xffff0000, v234
	v_lshlrev_b32_e32 v252, 16, v235
	v_and_b32_e32 v253, 0xffff0000, v235
	v_pk_fma_f32 v[218:219], v[110:111], v[250:251], v[218:219]
	v_pk_fma_f32 v[220:221], v[112:113], v[252:253], v[220:221]
	global_store_dwordx4 v194, v[218:221], s[54:55] offset:0
	v_pk_mul_f32 v[106:107], v[244:245], v[106:107] op_sel:[0,0] op_sel_hi:[0,1]
	v_pk_mul_f32 v[108:109], v[244:245], v[108:109] op_sel:[0,0] op_sel_hi:[0,1]
	v_pk_mul_f32 v[106:107], v[66:67], v[106:107]
	v_pk_mul_f32 v[108:109], v[68:69], v[108:109]
	v_mul_f32_e32 v106, v255, v106
	v_mul_f32_e32 v107, v255, v107
	v_mul_f32_e32 v108, v255, v108
	v_mul_f32_e32 v109, v255, v109
	v_exp_f32_e32 v106, v106
	v_exp_f32_e32 v107, v107
	v_exp_f32_e32 v108, v108
	v_exp_f32_e32 v109, v109
	v_add_f32_e32 v106, 1.0, v106
	v_add_f32_e32 v107, 1.0, v107
	v_add_f32_e32 v108, 1.0, v108
	v_add_f32_e32 v109, 1.0, v109
	v_rcp_f32_e32 v106, v106
	v_rcp_f32_e32 v107, v107
	v_rcp_f32_e32 v108, v108
	v_rcp_f32_e32 v109, v109
	s_waitcnt vmcnt(35)
	v_lshlrev_b32_e32 v250, 16, v236
	v_and_b32_e32 v251, 0xffff0000, v236
	v_lshlrev_b32_e32 v252, 16, v237
	v_and_b32_e32 v253, 0xffff0000, v237
	v_pk_fma_f32 v[222:223], v[106:107], v[250:251], v[222:223]
	v_pk_fma_f32 v[224:225], v[108:109], v[252:253], v[224:225]
	global_store_dwordx4 v194, v[222:225], s[54:55] offset:64
	v_pk_mul_f32 v[102:103], v[244:245], v[102:103] op_sel:[0,0] op_sel_hi:[0,1]
	v_pk_mul_f32 v[104:105], v[244:245], v[104:105] op_sel:[0,0] op_sel_hi:[0,1]
	v_pk_mul_f32 v[102:103], v[74:75], v[102:103]
	v_pk_mul_f32 v[104:105], v[76:77], v[104:105]
	v_mul_f32_e32 v102, v255, v102
	v_mul_f32_e32 v103, v255, v103
	v_mul_f32_e32 v104, v255, v104
	v_mul_f32_e32 v105, v255, v105
	v_exp_f32_e32 v102, v102
	v_exp_f32_e32 v103, v103
	v_exp_f32_e32 v104, v104
	v_exp_f32_e32 v105, v105
	v_add_f32_e32 v102, 1.0, v102
	v_add_f32_e32 v103, 1.0, v103
	v_add_f32_e32 v104, 1.0, v104
	v_add_f32_e32 v105, 1.0, v105
	v_rcp_f32_e32 v102, v102
	v_rcp_f32_e32 v103, v103
	v_rcp_f32_e32 v104, v104
	v_rcp_f32_e32 v105, v105
	s_waitcnt vmcnt(35)
	v_lshlrev_b32_e32 v250, 16, v238
	v_and_b32_e32 v251, 0xffff0000, v238
	v_lshlrev_b32_e32 v252, 16, v239
	v_and_b32_e32 v253, 0xffff0000, v239
	v_pk_fma_f32 v[226:227], v[102:103], v[250:251], v[226:227]
	v_pk_fma_f32 v[228:229], v[104:105], v[252:253], v[228:229]
	global_store_dwordx4 v194, v[226:229], s[54:55] offset:512
	v_pk_mul_f32 v[98:99], v[244:245], v[98:99] op_sel:[0,0] op_sel_hi:[0,1]
	v_pk_mul_f32 v[100:101], v[244:245], v[100:101] op_sel:[0,0] op_sel_hi:[0,1]
	v_pk_mul_f32 v[98:99], v[78:79], v[98:99]
	v_pk_mul_f32 v[100:101], v[80:81], v[100:101]
	v_mul_f32_e32 v98, v255, v98
	v_mul_f32_e32 v99, v255, v99
	v_mul_f32_e32 v100, v255, v100
	v_mul_f32_e32 v101, v255, v101
	v_exp_f32_e32 v98, v98
	v_exp_f32_e32 v99, v99
	v_exp_f32_e32 v100, v100
	v_exp_f32_e32 v101, v101
	v_add_f32_e32 v98, 1.0, v98
	v_add_f32_e32 v99, 1.0, v99
	v_add_f32_e32 v100, 1.0, v100
	v_add_f32_e32 v101, 1.0, v101
	v_rcp_f32_e32 v98, v98
	v_rcp_f32_e32 v99, v99
	v_rcp_f32_e32 v100, v100
	v_rcp_f32_e32 v101, v101
	s_waitcnt vmcnt(35)
	v_lshlrev_b32_e32 v250, 16, v240
	v_and_b32_e32 v251, 0xffff0000, v240
	v_lshlrev_b32_e32 v252, 16, v241
	v_and_b32_e32 v253, 0xffff0000, v241
	v_pk_fma_f32 v[230:231], v[98:99], v[250:251], v[230:231]
	v_pk_fma_f32 v[232:233], v[100:101], v[252:253], v[232:233]
	global_store_dwordx4 v194, v[230:233], s[54:55] offset:576
	v_add_u32_e32 v194, 0x280000, v190
	v_add_u32_e32 v195, 0x140000, v191
	global_load_dwordx4 v[218:221], v194, s[54:55] offset:0
	global_load_dwordx4 v[222:225], v194, s[54:55] offset:64
	global_load_dwordx4 v[226:229], v194, s[54:55] offset:512
	global_load_dwordx4 v[230:233], v194, s[54:55] offset:576
	global_load_dwordx2 v[234:235], v195, s[8:9] offset:0
	global_load_dwordx2 v[236:237], v195, s[8:9] offset:32
	global_load_dwordx2 v[238:239], v195, s[8:9] offset:256
	global_load_dwordx2 v[240:241], v195, s[8:9] offset:288
	v_add_u32_e32 v194, 0x2c0000, v190
	v_add_u32_e32 v195, 0x160000, v191
	global_load_dwordx4 v[110:113], v194, s[54:55] offset:0
	global_load_dwordx4 v[106:109], v194, s[54:55] offset:64
	global_load_dwordx4 v[102:105], v194, s[54:55] offset:512
	global_load_dwordx4 v[98:101], v194, s[54:55] offset:576
	global_load_dwordx2 v[118:119], v195, s[8:9] offset:0
	global_load_dwordx2 v[120:121], v195, s[8:9] offset:32
	global_load_dwordx2 v[114:115], v195, s[8:9] offset:256
	global_load_dwordx2 v[116:117], v195, s[8:9] offset:288
	v_add_u32_e32 v194, 0xc0000, v190
	v_pk_mul_f32 v[94:95], v[244:245], v[94:95] op_sel:[1,0] op_sel_hi:[1,1]
	v_pk_mul_f32 v[96:97], v[244:245], v[96:97] op_sel:[1,0] op_sel_hi:[1,1]
	v_pk_mul_f32 v[94:95], v[58:59], v[94:95]
	v_pk_mul_f32 v[96:97], v[60:61], v[96:97]
	v_mul_f32_e32 v94, v255, v94
	v_mul_f32_e32 v95, v255, v95
	v_mul_f32_e32 v96, v255, v96
	v_mul_f32_e32 v97, v255, v97
	v_exp_f32_e32 v94, v94
	v_exp_f32_e32 v95, v95
	v_exp_f32_e32 v96, v96
	v_exp_f32_e32 v97, v97
	v_add_f32_e32 v94, 1.0, v94
	v_add_f32_e32 v95, 1.0, v95
	v_add_f32_e32 v96, 1.0, v96
	v_add_f32_e32 v97, 1.0, v97
	v_rcp_f32_e32 v94, v94
	v_rcp_f32_e32 v95, v95
	v_rcp_f32_e32 v96, v96
	v_rcp_f32_e32 v97, v97
	s_waitcnt vmcnt(43)
; __device__ __forceinline__ unsigned cvt_pk_bf16(float lo, float hi) { unsigned r; asm volatile("s_nop 0\n\tv_cvt_pk_bf16_f32 %0, %1, %2" : "=v"(r) : "v"(lo), "v"(hi)); return r; }
; __device__ __forceinline__ f32x4 sig4(const f32x4 v) { return (f32x4){sigmoidf_(v[0]), sigmoidf_(v[1]), sigmoidf_(v[2]), sigmoidf_(v[3])}; }
;     __device__ __forceinline__ void operator()(const typename AccT<I8>::type (&acc)[2][2][4][2], const Unit& u, int wr, int wc, int fr, int fq) const {
;     ...
;         for (int s = 0; s < 8; ++s) { const int ai = s >> 2, m = s & 3; const int r = row0 + ai * HALF + m * 16; const size_t off = (size_t)r * 4096 + col0;
;                 if (s + 1 < 8) load_row(nxt, (size_t)(row0 + ((s + 1) >> 2) * HALF + ((s + 1) & 3) * 16) * 4096 + col0);
;                 const float rs = rsv[s];
;                 float ss = 0.f, mx = 0.f;
; #pragma unroll
;                 for (int bj = 0; bj < 2; ++bj)
; #pragma unroll
;                     for (int n = 0; n < 2; ++n) { const size_t o = off + bj * HALF + n * 16; const f32x4 b = cur.b[bj][n]; f32x4 v;
;                         if constexpr (I8) v = __builtin_convertvector(acc[ai][bj][m][n], f32x4) * rs * sv[bj][n]; else v = acc[ai][bj][m][n];
;                         if (MODE == 1) { const u32x2 pw = cur.pw[bj][n]; const f32x4 pp = (f32x4){bf_lo(pw.x), bf_hi(pw.x), bf_lo(pw.y), bf_hi(pw.y)}; v = sig4(I8 ? v : v * rs) * pp; }
;                         const f32x4 x = b + v; *(f32x4*)(out + o) = x;
;                         if (MODE == 0 && XB) { u32x2 w; w.x = cvt_pk_bf16(x[0], x[1]); w.y = cvt_pk_bf16(x[2], x[3]); *(u32x2*)(XB + o) = w; ss += (x[0] * x[0] + x[1] * x[1]) + (x[2] * x[2] + x[3] * x[3]);
;                             if (RM) mx = fmaxf(fmaxf(mx, fmaxf(fabsf(x[0]), fabsf(x[1]))), fmaxf(fabsf(x[2]), fabsf(x[3]))); } }
;                 if (MODE == 0 && XB) { ss += __shfl_xor(ss, 16); ss += __shfl_xor(ss, 32); if (fq == 0) unsafeAtomicAdd(SS + r, ss);
;                     if (RM) { mx = fmaxf(mx, __shfl_xor(mx, 16)); mx = fmaxf(mx, __shfl_xor(mx, 32)); if (fq == 0) atomicMax(RM + r, __builtin_bit_cast(unsigned, mx)); } }
;                 cur = nxt; }
	v_lshlrev_b32_e32 v250, 16, v162
	v_and_b32_e32 v251, 0xffff0000, v162
	v_lshlrev_b32_e32 v252, 16, v163
	v_and_b32_e32 v253, 0xffff0000, v163
	v_pk_fma_f32 v[146:147], v[94:95], v[250:251], v[146:147]
	v_pk_fma_f32 v[148:149], v[96:97], v[252:253], v[148:149]
	global_store_dwordx4 v194, v[146:149], s[54:55] offset:0
	v_pk_mul_f32 v[90:91], v[244:245], v[90:91] op_sel:[1,0] op_sel_hi:[1,1]
	v_pk_mul_f32 v[92:93], v[244:245], v[92:93] op_sel:[1,0] op_sel_hi:[1,1]
	v_pk_mul_f32 v[90:91], v[66:67], v[90:91]
	v_pk_mul_f32 v[92:93], v[68:69], v[92:93]
	v_mul_f32_e32 v90, v255, v90
	v_mul_f32_e32 v91, v255, v91
	v_mul_f32_e32 v92, v255, v92
	v_mul_f32_e32 v93, v255, v93
	v_exp_f32_e32 v90, v90
	v_exp_f32_e32 v91, v91
	v_exp_f32_e32 v92, v92
	v_exp_f32_e32 v93, v93
	v_add_f32_e32 v90, 1.0, v90
	v_add_f32_e32 v91, 1.0, v91
	v_add_f32_e32 v92, 1.0, v92
	v_add_f32_e32 v93, 1.0, v93
	v_rcp_f32_e32 v90, v90
	v_rcp_f32_e32 v91, v91
	v_rcp_f32_e32 v92, v92
	v_rcp_f32_e32 v93, v93
	s_waitcnt vmcnt(43)
	v_lshlrev_b32_e32 v250, 16, v164
	v_and_b32_e32 v251, 0xffff0000, v164
	v_lshlrev_b32_e32 v252, 16, v165
	v_and_b32_e32 v253, 0xffff0000, v165
	v_pk_fma_f32 v[150:151], v[90:91], v[250:251], v[150:151]
	v_pk_fma_f32 v[152:153], v[92:93], v[252:253], v[152:153]
	global_store_dwordx4 v194, v[150:153], s[54:55] offset:64
	v_pk_mul_f32 v[86:87], v[244:245], v[86:87] op_sel:[1,0] op_sel_hi:[1,1]
	v_pk_mul_f32 v[88:89], v[244:245], v[88:89] op_sel:[1,0] op_sel_hi:[1,1]
	v_pk_mul_f32 v[86:87], v[74:75], v[86:87]
	v_pk_mul_f32 v[88:89], v[76:77], v[88:89]
	v_mul_f32_e32 v86, v255, v86
	v_mul_f32_e32 v87, v255, v87
	v_mul_f32_e32 v88, v255, v88
	v_mul_f32_e32 v89, v255, v89
	v_exp_f32_e32 v86, v86
	v_exp_f32_e32 v87, v87
	v_exp_f32_e32 v88, v88
	v_exp_f32_e32 v89, v89
	v_add_f32_e32 v86, 1.0, v86
	v_add_f32_e32 v87, 1.0, v87
	v_add_f32_e32 v88, 1.0, v88
	v_add_f32_e32 v89, 1.0, v89
	v_rcp_f32_e32 v86, v86
	v_rcp_f32_e32 v87, v87
	v_rcp_f32_e32 v88, v88
	v_rcp_f32_e32 v89, v89
	s_waitcnt vmcnt(43)
	v_lshlrev_b32_e32 v250, 16, v178
	v_and_b32_e32 v251, 0xffff0000, v178
	v_lshlrev_b32_e32 v252, 16, v179
	v_and_b32_e32 v253, 0xffff0000, v179
	v_pk_fma_f32 v[154:155], v[86:87], v[250:251], v[154:155]
	v_pk_fma_f32 v[156:157], v[88:89], v[252:253], v[156:157]
	global_store_dwordx4 v194, v[154:157], s[54:55] offset:512
	v_pk_mul_f32 v[82:83], v[244:245], v[82:83] op_sel:[1,0] op_sel_hi:[1,1]
	v_pk_mul_f32 v[84:85], v[244:245], v[84:85] op_sel:[1,0] op_sel_hi:[1,1]
	v_pk_mul_f32 v[82:83], v[78:79], v[82:83]
	v_pk_mul_f32 v[84:85], v[80:81], v[84:85]
	v_mul_f32_e32 v82, v255, v82
	v_mul_f32_e32 v83, v255, v83
	v_mul_f32_e32 v84, v255, v84
	v_mul_f32_e32 v85, v255, v85
	v_exp_f32_e32 v82, v82
	v_exp_f32_e32 v83, v83
	v_exp_f32_e32 v84, v84
	v_exp_f32_e32 v85, v85
	v_add_f32_e32 v82, 1.0, v82
	v_add_f32_e32 v83, 1.0, v83
	v_add_f32_e32 v84, 1.0, v84
	v_add_f32_e32 v85, 1.0, v85
	v_rcp_f32_e32 v82, v82
	v_rcp_f32_e32 v83, v83
	v_rcp_f32_e32 v84, v84
	v_rcp_f32_e32 v85, v85
	s_waitcnt vmcnt(43)
	v_lshlrev_b32_e32 v250, 16, v180
	v_and_b32_e32 v251, 0xffff0000, v180
	v_lshlrev_b32_e32 v252, 16, v181
	v_and_b32_e32 v253, 0xffff0000, v181
	v_pk_fma_f32 v[158:159], v[82:83], v[250:251], v[158:159]
	v_pk_fma_f32 v[160:161], v[84:85], v[252:253], v[160:161]
	global_store_dwordx4 v194, v[158:161], s[54:55] offset:576
	v_add_u32_e32 v194, 0x200000, v190
	v_pk_mul_f32 v[70:71], v[246:247], v[70:71] op_sel:[0,0] op_sel_hi:[0,1]
	v_pk_mul_f32 v[72:73], v[246:247], v[72:73] op_sel:[0,0] op_sel_hi:[0,1]
	v_pk_mul_f32 v[70:71], v[58:59], v[70:71]
	v_pk_mul_f32 v[72:73], v[60:61], v[72:73]
	v_mul_f32_e32 v70, v255, v70
	v_mul_f32_e32 v71, v255, v71
	v_mul_f32_e32 v72, v255, v72
	v_mul_f32_e32 v73, v255, v73
	v_exp_f32_e32 v70, v70
	v_exp_f32_e32 v71, v71
	v_exp_f32_e32 v72, v72
	v_exp_f32_e32 v73, v73
	v_add_f32_e32 v70, 1.0, v70
	v_add_f32_e32 v71, 1.0, v71
	v_add_f32_e32 v72, 1.0, v72
	v_add_f32_e32 v73, 1.0, v73
	v_rcp_f32_e32 v70, v70
	v_rcp_f32_e32 v71, v71
	v_rcp_f32_e32 v72, v72
	v_rcp_f32_e32 v73, v73
	s_waitcnt vmcnt(35)
	v_lshlrev_b32_e32 v250, 16, v184
	v_and_b32_e32 v251, 0xffff0000, v184
	v_lshlrev_b32_e32 v252, 16, v185
	v_and_b32_e32 v253, 0xffff0000, v185
	v_pk_fma_f32 v[198:199], v[70:71], v[250:251], v[198:199]
	v_pk_fma_f32 v[200:201], v[72:73], v[252:253], v[200:201]
	global_store_dwordx4 v194, v[198:201], s[54:55] offset:0
	v_pk_mul_f32 v[62:63], v[246:247], v[62:63] op_sel:[0,0] op_sel_hi:[0,1]
	v_pk_mul_f32 v[64:65], v[246:247], v[64:65] op_sel:[0,0] op_sel_hi:[0,1]
	v_pk_mul_f32 v[62:63], v[66:67], v[62:63]
	v_pk_mul_f32 v[64:65], v[68:69], v[64:65]
	v_mul_f32_e32 v62, v255, v62
	v_mul_f32_e32 v63, v255, v63
	v_mul_f32_e32 v64, v255, v64
	v_mul_f32_e32 v65, v255, v65
	v_exp_f32_e32 v62, v62
	v_exp_f32_e32 v63, v63
	v_exp_f32_e32 v64, v64
	v_exp_f32_e32 v65, v65
	v_add_f32_e32 v62, 1.0, v62
	v_add_f32_e32 v63, 1.0, v63
	v_add_f32_e32 v64, 1.0, v64
	v_add_f32_e32 v65, 1.0, v65
	v_rcp_f32_e32 v62, v62
	v_rcp_f32_e32 v63, v63
	v_rcp_f32_e32 v64, v64
	v_rcp_f32_e32 v65, v65
	s_waitcnt vmcnt(35)
	v_lshlrev_b32_e32 v250, 16, v186
	v_and_b32_e32 v251, 0xffff0000, v186
	v_lshlrev_b32_e32 v252, 16, v187
	v_and_b32_e32 v253, 0xffff0000, v187
	v_pk_fma_f32 v[202:203], v[62:63], v[250:251], v[202:203]
	v_pk_fma_f32 v[204:205], v[64:65], v[252:253], v[204:205]
	global_store_dwordx4 v194, v[202:205], s[54:55] offset:64
	v_pk_mul_f32 v[54:55], v[246:247], v[54:55] op_sel:[0,0] op_sel_hi:[0,1]
	v_pk_mul_f32 v[56:57], v[246:247], v[56:57] op_sel:[0,0] op_sel_hi:[0,1]
	v_pk_mul_f32 v[54:55], v[74:75], v[54:55]
	v_pk_mul_f32 v[56:57], v[76:77], v[56:57]
	v_mul_f32_e32 v54, v255, v54
	v_mul_f32_e32 v55, v255, v55
	v_mul_f32_e32 v56, v255, v56
	v_mul_f32_e32 v57, v255, v57
	v_exp_f32_e32 v54, v54
	v_exp_f32_e32 v55, v55
	v_exp_f32_e32 v56, v56
	v_exp_f32_e32 v57, v57
	v_add_f32_e32 v54, 1.0, v54
	v_add_f32_e32 v55, 1.0, v55
	v_add_f32_e32 v56, 1.0, v56
	v_add_f32_e32 v57, 1.0, v57
	v_rcp_f32_e32 v54, v54
	v_rcp_f32_e32 v55, v55
	v_rcp_f32_e32 v56, v56
	v_rcp_f32_e32 v57, v57
	s_waitcnt vmcnt(35)
; __device__ __forceinline__ unsigned cvt_pk_bf16(float lo, float hi) { unsigned r; asm volatile("s_nop 0\n\tv_cvt_pk_bf16_f32 %0, %1, %2" : "=v"(r) : "v"(lo), "v"(hi)); return r; }
; __device__ __forceinline__ f32x4 sig4(const f32x4 v) { return (f32x4){sigmoidf_(v[0]), sigmoidf_(v[1]), sigmoidf_(v[2]), sigmoidf_(v[3])}; }
;     __device__ __forceinline__ void operator()(const typename AccT<I8>::type (&acc)[2][2][4][2], const Unit& u, int wr, int wc, int fr, int fq) const {
;     ...
;         for (int s = 0; s < 8; ++s) { const int ai = s >> 2, m = s & 3; const int r = row0 + ai * HALF + m * 16; const size_t off = (size_t)r * 4096 + col0;
;                 if (s + 1 < 8) load_row(nxt, (size_t)(row0 + ((s + 1) >> 2) * HALF + ((s + 1) & 3) * 16) * 4096 + col0);
;                 const float rs = rsv[s];
;                 float ss = 0.f, mx = 0.f;
; #pragma unroll
;                 for (int bj = 0; bj < 2; ++bj)
; #pragma unroll
;                     for (int n = 0; n < 2; ++n) { const size_t o = off + bj * HALF + n * 16; const f32x4 b = cur.b[bj][n]; f32x4 v;
;                         if constexpr (I8) v = __builtin_convertvector(acc[ai][bj][m][n], f32x4) * rs * sv[bj][n]; else v = acc[ai][bj][m][n];
;                         if (MODE == 1) { const u32x2 pw = cur.pw[bj][n]; const f32x4 pp = (f32x4){bf_lo(pw.x), bf_hi(pw.x), bf_lo(pw.y), bf_hi(pw.y)}; v = sig4(I8 ? v : v * rs) * pp; }
;                         const f32x4 x = b + v; *(f32x4*)(out + o) = x;
;                         if (MODE == 0 && XB) { u32x2 w; w.x = cvt_pk_bf16(x[0], x[1]); w.y = cvt_pk_bf16(x[2], x[3]); *(u32x2*)(XB + o) = w; ss += (x[0] * x[0] + x[1] * x[1]) + (x[2] * x[2] + x[3] * x[3]);
;                             if (RM) mx = fmaxf(fmaxf(mx, fmaxf(fabsf(x[0]), fabsf(x[1]))), fmaxf(fabsf(x[2]), fabsf(x[3]))); } }
;                 if (MODE == 0 && XB) { ss += __shfl_xor(ss, 16); ss += __shfl_xor(ss, 32); if (fq == 0) unsafeAtomicAdd(SS + r, ss);
;                     if (RM) { mx = fmaxf(mx, __shfl_xor(mx, 16)); mx = fmaxf(mx, __shfl_xor(mx, 32)); if (fq == 0) atomicMax(RM + r, __builtin_bit_cast(unsigned, mx)); } }
;                 cur = nxt; }
	v_lshlrev_b32_e32 v250, 16, v214
	v_and_b32_e32 v251, 0xffff0000, v214
	v_lshlrev_b32_e32 v252, 16, v215
	v_and_b32_e32 v253, 0xffff0000, v215
	v_pk_fma_f32 v[206:207], v[54:55], v[250:251], v[206:207]
	v_pk_fma_f32 v[208:209], v[56:57], v[252:253], v[208:209]
	global_store_dwordx4 v194, v[206:209], s[54:55] offset:512
	v_pk_mul_f32 v[50:51], v[246:247], v[50:51] op_sel:[0,0] op_sel_hi:[0,1]
	v_pk_mul_f32 v[52:53], v[246:247], v[52:53] op_sel:[0,0] op_sel_hi:[0,1]
	v_pk_mul_f32 v[50:51], v[78:79], v[50:51]
	v_pk_mul_f32 v[52:53], v[80:81], v[52:53]
	v_mul_f32_e32 v50, v255, v50
	v_mul_f32_e32 v51, v255, v51
	v_mul_f32_e32 v52, v255, v52
	v_mul_f32_e32 v53, v255, v53
	v_exp_f32_e32 v50, v50
	v_exp_f32_e32 v51, v51
	v_exp_f32_e32 v52, v52
	v_exp_f32_e32 v53, v53
	v_add_f32_e32 v50, 1.0, v50
	v_add_f32_e32 v51, 1.0, v51
	v_add_f32_e32 v52, 1.0, v52
	v_add_f32_e32 v53, 1.0, v53
	v_rcp_f32_e32 v50, v50
	v_rcp_f32_e32 v51, v51
	v_rcp_f32_e32 v52, v52
	v_rcp_f32_e32 v53, v53
	s_waitcnt vmcnt(35)
	v_lshlrev_b32_e32 v250, 16, v216
	v_and_b32_e32 v251, 0xffff0000, v216
	v_lshlrev_b32_e32 v252, 16, v217
	v_and_b32_e32 v253, 0xffff0000, v217
	v_pk_fma_f32 v[210:211], v[50:51], v[250:251], v[210:211]
	v_pk_fma_f32 v[212:213], v[52:53], v[252:253], v[212:213]
	global_store_dwordx4 v194, v[210:213], s[54:55] offset:576
	v_add_u32_e32 v194, 0x240000, v190
	v_pk_mul_f32 v[46:47], v[246:247], v[46:47] op_sel:[1,0] op_sel_hi:[1,1]
	v_pk_mul_f32 v[48:49], v[246:247], v[48:49] op_sel:[1,0] op_sel_hi:[1,1]
	v_pk_mul_f32 v[46:47], v[58:59], v[46:47]
	v_pk_mul_f32 v[48:49], v[60:61], v[48:49]
	v_mul_f32_e32 v46, v255, v46
	v_mul_f32_e32 v47, v255, v47
	v_mul_f32_e32 v48, v255, v48
	v_mul_f32_e32 v49, v255, v49
	v_exp_f32_e32 v46, v46
	v_exp_f32_e32 v47, v47
	v_exp_f32_e32 v48, v48
	v_exp_f32_e32 v49, v49
	v_add_f32_e32 v46, 1.0, v46
	v_add_f32_e32 v47, 1.0, v47
	v_add_f32_e32 v48, 1.0, v48
	v_add_f32_e32 v49, 1.0, v49
	v_rcp_f32_e32 v46, v46
	v_rcp_f32_e32 v47, v47
	v_rcp_f32_e32 v48, v48
	v_rcp_f32_e32 v49, v49
	s_waitcnt vmcnt(31)
	v_lshlrev_b32_e32 v250, 16, v126
	v_and_b32_e32 v251, 0xffff0000, v126
	v_lshlrev_b32_e32 v252, 16, v127
	v_and_b32_e32 v253, 0xffff0000, v127
	v_pk_fma_f32 v[142:143], v[46:47], v[250:251], v[142:143]
	v_pk_fma_f32 v[144:145], v[48:49], v[252:253], v[144:145]
	global_store_dwordx4 v194, v[142:145], s[54:55] offset:0
	v_pk_mul_f32 v[42:43], v[246:247], v[42:43] op_sel:[1,0] op_sel_hi:[1,1]
	v_pk_mul_f32 v[44:45], v[246:247], v[44:45] op_sel:[1,0] op_sel_hi:[1,1]
	v_pk_mul_f32 v[42:43], v[66:67], v[42:43]
	v_pk_mul_f32 v[44:45], v[68:69], v[44:45]
	v_mul_f32_e32 v42, v255, v42
	v_mul_f32_e32 v43, v255, v43
	v_mul_f32_e32 v44, v255, v44
	v_mul_f32_e32 v45, v255, v45
	v_exp_f32_e32 v42, v42
	v_exp_f32_e32 v43, v43
	v_exp_f32_e32 v44, v44
	v_exp_f32_e32 v45, v45
	v_add_f32_e32 v42, 1.0, v42
	v_add_f32_e32 v43, 1.0, v43
	v_add_f32_e32 v44, 1.0, v44
	v_add_f32_e32 v45, 1.0, v45
	v_rcp_f32_e32 v42, v42
	v_rcp_f32_e32 v43, v43
	v_rcp_f32_e32 v44, v44
	v_rcp_f32_e32 v45, v45
	s_waitcnt vmcnt(31)
	v_lshlrev_b32_e32 v250, 16, v128
	v_and_b32_e32 v251, 0xffff0000, v128
	v_lshlrev_b32_e32 v252, 16, v129
	v_and_b32_e32 v253, 0xffff0000, v129
	v_pk_fma_f32 v[138:139], v[42:43], v[250:251], v[138:139]
	v_pk_fma_f32 v[140:141], v[44:45], v[252:253], v[140:141]
	global_store_dwordx4 v194, v[138:141], s[54:55] offset:64
	v_pk_mul_f32 v[38:39], v[246:247], v[38:39] op_sel:[1,0] op_sel_hi:[1,1]
	v_pk_mul_f32 v[40:41], v[246:247], v[40:41] op_sel:[1,0] op_sel_hi:[1,1]
	v_pk_mul_f32 v[38:39], v[74:75], v[38:39]
	v_pk_mul_f32 v[40:41], v[76:77], v[40:41]
	v_mul_f32_e32 v38, v255, v38
	v_mul_f32_e32 v39, v255, v39
	v_mul_f32_e32 v40, v255, v40
	v_mul_f32_e32 v41, v255, v41
	v_exp_f32_e32 v38, v38
	v_exp_f32_e32 v39, v39
	v_exp_f32_e32 v40, v40
	v_exp_f32_e32 v41, v41
	v_add_f32_e32 v38, 1.0, v38
	v_add_f32_e32 v39, 1.0, v39
	v_add_f32_e32 v40, 1.0, v40
	v_add_f32_e32 v41, 1.0, v41
	v_rcp_f32_e32 v38, v38
	v_rcp_f32_e32 v39, v39
	v_rcp_f32_e32 v40, v40
	v_rcp_f32_e32 v41, v41
	s_waitcnt vmcnt(31)
	v_lshlrev_b32_e32 v250, 16, v122
	v_and_b32_e32 v251, 0xffff0000, v122
	v_lshlrev_b32_e32 v252, 16, v123
	v_and_b32_e32 v253, 0xffff0000, v123
	v_pk_fma_f32 v[134:135], v[38:39], v[250:251], v[134:135]
	v_pk_fma_f32 v[136:137], v[40:41], v[252:253], v[136:137]
	global_store_dwordx4 v194, v[134:137], s[54:55] offset:512
	v_pk_mul_f32 v[34:35], v[246:247], v[34:35] op_sel:[1,0] op_sel_hi:[1,1]
	v_pk_mul_f32 v[36:37], v[246:247], v[36:37] op_sel:[1,0] op_sel_hi:[1,1]
	v_pk_mul_f32 v[34:35], v[78:79], v[34:35]
	v_pk_mul_f32 v[36:37], v[80:81], v[36:37]
	v_mul_f32_e32 v34, v255, v34
	v_mul_f32_e32 v35, v255, v35
	v_mul_f32_e32 v36, v255, v36
	v_mul_f32_e32 v37, v255, v37
	v_exp_f32_e32 v34, v34
	v_exp_f32_e32 v35, v35
	v_exp_f32_e32 v36, v36
	v_exp_f32_e32 v37, v37
	v_add_f32_e32 v34, 1.0, v34
	v_add_f32_e32 v35, 1.0, v35
	v_add_f32_e32 v36, 1.0, v36
	v_add_f32_e32 v37, 1.0, v37
	v_rcp_f32_e32 v34, v34
	v_rcp_f32_e32 v35, v35
	v_rcp_f32_e32 v36, v36
	v_rcp_f32_e32 v37, v37
	s_waitcnt vmcnt(31)
	v_lshlrev_b32_e32 v250, 16, v124
	v_and_b32_e32 v251, 0xffff0000, v124
	v_lshlrev_b32_e32 v252, 16, v125
	v_and_b32_e32 v253, 0xffff0000, v125
	v_pk_fma_f32 v[130:131], v[34:35], v[250:251], v[130:131]
	v_pk_fma_f32 v[132:133], v[36:37], v[252:253], v[132:133]
	global_store_dwordx4 v194, v[130:133], s[54:55] offset:576
	v_add_u32_e32 v194, 0x280000, v190
	v_pk_mul_f32 v[30:31], v[248:249], v[30:31] op_sel:[0,0] op_sel_hi:[0,1]
	v_pk_mul_f32 v[32:33], v[248:249], v[32:33] op_sel:[0,0] op_sel_hi:[0,1]
	v_pk_mul_f32 v[30:31], v[58:59], v[30:31]
	v_pk_mul_f32 v[32:33], v[60:61], v[32:33]
	v_mul_f32_e32 v30, v255, v30
	v_mul_f32_e32 v31, v255, v31
	v_mul_f32_e32 v32, v255, v32
	v_mul_f32_e32 v33, v255, v33
	v_exp_f32_e32 v30, v30
	v_exp_f32_e32 v31, v31
	v_exp_f32_e32 v32, v32
	v_exp_f32_e32 v33, v33
	v_add_f32_e32 v30, 1.0, v30
	v_add_f32_e32 v31, 1.0, v31
	v_add_f32_e32 v32, 1.0, v32
	v_add_f32_e32 v33, 1.0, v33
	v_rcp_f32_e32 v30, v30
	v_rcp_f32_e32 v31, v31
	v_rcp_f32_e32 v32, v32
	v_rcp_f32_e32 v33, v33
	s_waitcnt vmcnt(23)
; __device__ __forceinline__ unsigned cvt_pk_bf16(float lo, float hi) { unsigned r; asm volatile("s_nop 0\n\tv_cvt_pk_bf16_f32 %0, %1, %2" : "=v"(r) : "v"(lo), "v"(hi)); return r; }
; __device__ __forceinline__ f32x4 sig4(const f32x4 v) { return (f32x4){sigmoidf_(v[0]), sigmoidf_(v[1]), sigmoidf_(v[2]), sigmoidf_(v[3])}; }
;     __device__ __forceinline__ void operator()(const typename AccT<I8>::type (&acc)[2][2][4][2], const Unit& u, int wr, int wc, int fr, int fq) const {
;     ...
;         for (int s = 0; s < 8; ++s) { const int ai = s >> 2, m = s & 3; const int r = row0 + ai * HALF + m * 16; const size_t off = (size_t)r * 4096 + col0;
;                 if (s + 1 < 8) load_row(nxt, (size_t)(row0 + ((s + 1) >> 2) * HALF + ((s + 1) & 3) * 16) * 4096 + col0);
;                 const float rs = rsv[s];
;                 float ss = 0.f, mx = 0.f;
; #pragma unroll
;                 for (int bj = 0; bj < 2; ++bj)
; #pragma unroll
;                     for (int n = 0; n < 2; ++n) { const size_t o = off + bj * HALF + n * 16; const f32x4 b = cur.b[bj][n]; f32x4 v;
;                         if constexpr (I8) v = __builtin_convertvector(acc[ai][bj][m][n], f32x4) * rs * sv[bj][n]; else v = acc[ai][bj][m][n];
;                         if (MODE == 1) { const u32x2 pw = cur.pw[bj][n]; const f32x4 pp = (f32x4){bf_lo(pw.x), bf_hi(pw.x), bf_lo(pw.y), bf_hi(pw.y)}; v = sig4(I8 ? v : v * rs) * pp; }
;                         const f32x4 x = b + v; *(f32x4*)(out + o) = x;
;                         if (MODE == 0 && XB) { u32x2 w; w.x = cvt_pk_bf16(x[0], x[1]); w.y = cvt_pk_bf16(x[2], x[3]); *(u32x2*)(XB + o) = w; ss += (x[0] * x[0] + x[1] * x[1]) + (x[2] * x[2] + x[3] * x[3]);
;                             if (RM) mx = fmaxf(fmaxf(mx, fmaxf(fabsf(x[0]), fabsf(x[1]))), fmaxf(fabsf(x[2]), fabsf(x[3]))); } }
;                 if (MODE == 0 && XB) { ss += __shfl_xor(ss, 16); ss += __shfl_xor(ss, 32); if (fq == 0) unsafeAtomicAdd(SS + r, ss);
;                     if (RM) { mx = fmaxf(mx, __shfl_xor(mx, 16)); mx = fmaxf(mx, __shfl_xor(mx, 32)); if (fq == 0) atomicMax(RM + r, __builtin_bit_cast(unsigned, mx)); } }
;                 cur = nxt; }
	v_lshlrev_b32_e32 v250, 16, v234
	v_and_b32_e32 v251, 0xffff0000, v234
	v_lshlrev_b32_e32 v252, 16, v235
	v_and_b32_e32 v253, 0xffff0000, v235
	v_pk_fma_f32 v[218:219], v[30:31], v[250:251], v[218:219]
	v_pk_fma_f32 v[220:221], v[32:33], v[252:253], v[220:221]
	global_store_dwordx4 v194, v[218:221], s[54:55] offset:0
	v_pk_mul_f32 v[26:27], v[248:249], v[26:27] op_sel:[0,0] op_sel_hi:[0,1]
	v_pk_mul_f32 v[28:29], v[248:249], v[28:29] op_sel:[0,0] op_sel_hi:[0,1]
	v_pk_mul_f32 v[26:27], v[66:67], v[26:27]
	v_pk_mul_f32 v[28:29], v[68:69], v[28:29]
	v_mul_f32_e32 v26, v255, v26
	v_mul_f32_e32 v27, v255, v27
	v_mul_f32_e32 v28, v255, v28
	v_mul_f32_e32 v29, v255, v29
	v_exp_f32_e32 v26, v26
	v_exp_f32_e32 v27, v27
	v_exp_f32_e32 v28, v28
	v_exp_f32_e32 v29, v29
	v_add_f32_e32 v26, 1.0, v26
	v_add_f32_e32 v27, 1.0, v27
	v_add_f32_e32 v28, 1.0, v28
	v_add_f32_e32 v29, 1.0, v29
	v_rcp_f32_e32 v26, v26
	v_rcp_f32_e32 v27, v27
	v_rcp_f32_e32 v28, v28
	v_rcp_f32_e32 v29, v29
	s_waitcnt vmcnt(23)
	v_lshlrev_b32_e32 v250, 16, v236
	v_and_b32_e32 v251, 0xffff0000, v236
	v_lshlrev_b32_e32 v252, 16, v237
	v_and_b32_e32 v253, 0xffff0000, v237
	v_pk_fma_f32 v[222:223], v[26:27], v[250:251], v[222:223]
	v_pk_fma_f32 v[224:225], v[28:29], v[252:253], v[224:225]
	global_store_dwordx4 v194, v[222:225], s[54:55] offset:64
	v_pk_mul_f32 v[22:23], v[248:249], v[22:23] op_sel:[0,0] op_sel_hi:[0,1]
	v_pk_mul_f32 v[24:25], v[248:249], v[24:25] op_sel:[0,0] op_sel_hi:[0,1]
	v_pk_mul_f32 v[22:23], v[74:75], v[22:23]
	v_pk_mul_f32 v[24:25], v[76:77], v[24:25]
	v_mul_f32_e32 v22, v255, v22
	v_mul_f32_e32 v23, v255, v23
	v_mul_f32_e32 v24, v255, v24
	v_mul_f32_e32 v25, v255, v25
	v_exp_f32_e32 v22, v22
	v_exp_f32_e32 v23, v23
	v_exp_f32_e32 v24, v24
	v_exp_f32_e32 v25, v25
	v_add_f32_e32 v22, 1.0, v22
	v_add_f32_e32 v23, 1.0, v23
	v_add_f32_e32 v24, 1.0, v24
	v_add_f32_e32 v25, 1.0, v25
	v_rcp_f32_e32 v22, v22
	v_rcp_f32_e32 v23, v23
	v_rcp_f32_e32 v24, v24
	v_rcp_f32_e32 v25, v25
	s_waitcnt vmcnt(23)
	v_lshlrev_b32_e32 v250, 16, v238
	v_and_b32_e32 v251, 0xffff0000, v238
	v_lshlrev_b32_e32 v252, 16, v239
	v_and_b32_e32 v253, 0xffff0000, v239
	v_pk_fma_f32 v[226:227], v[22:23], v[250:251], v[226:227]
	v_pk_fma_f32 v[228:229], v[24:25], v[252:253], v[228:229]
	global_store_dwordx4 v194, v[226:229], s[54:55] offset:512
	v_pk_mul_f32 v[18:19], v[248:249], v[18:19] op_sel:[0,0] op_sel_hi:[0,1]
	v_pk_mul_f32 v[20:21], v[248:249], v[20:21] op_sel:[0,0] op_sel_hi:[0,1]
	v_pk_mul_f32 v[18:19], v[78:79], v[18:19]
	v_pk_mul_f32 v[20:21], v[80:81], v[20:21]
	v_mul_f32_e32 v18, v255, v18
	v_mul_f32_e32 v19, v255, v19
	v_mul_f32_e32 v20, v255, v20
	v_mul_f32_e32 v21, v255, v21
	v_exp_f32_e32 v18, v18
	v_exp_f32_e32 v19, v19
	v_exp_f32_e32 v20, v20
	v_exp_f32_e32 v21, v21
	v_add_f32_e32 v18, 1.0, v18
	v_add_f32_e32 v19, 1.0, v19
	v_add_f32_e32 v20, 1.0, v20
	v_add_f32_e32 v21, 1.0, v21
	v_rcp_f32_e32 v18, v18
	v_rcp_f32_e32 v19, v19
	v_rcp_f32_e32 v20, v20
	v_rcp_f32_e32 v21, v21
	s_waitcnt vmcnt(23)
	v_lshlrev_b32_e32 v250, 16, v240
	v_and_b32_e32 v251, 0xffff0000, v240
	v_lshlrev_b32_e32 v252, 16, v241
	v_and_b32_e32 v253, 0xffff0000, v241
	v_pk_fma_f32 v[230:231], v[18:19], v[250:251], v[230:231]
	v_pk_fma_f32 v[232:233], v[20:21], v[252:253], v[232:233]
	global_store_dwordx4 v194, v[230:233], s[54:55] offset:576
	v_add_u32_e32 v194, 0x2c0000, v190
	v_pk_mul_f32 v[14:15], v[248:249], v[14:15] op_sel:[1,0] op_sel_hi:[1,1]
	v_pk_mul_f32 v[16:17], v[248:249], v[16:17] op_sel:[1,0] op_sel_hi:[1,1]
	v_pk_mul_f32 v[14:15], v[58:59], v[14:15]
	v_pk_mul_f32 v[16:17], v[60:61], v[16:17]
	v_mul_f32_e32 v14, v255, v14
	v_mul_f32_e32 v15, v255, v15
	v_mul_f32_e32 v16, v255, v16
	v_mul_f32_e32 v17, v255, v17
	v_exp_f32_e32 v14, v14
	v_exp_f32_e32 v15, v15
	v_exp_f32_e32 v16, v16
	v_exp_f32_e32 v17, v17
	v_add_f32_e32 v14, 1.0, v14
	v_add_f32_e32 v15, 1.0, v15
	v_add_f32_e32 v16, 1.0, v16
	v_add_f32_e32 v17, 1.0, v17
	v_rcp_f32_e32 v14, v14
	v_rcp_f32_e32 v15, v15
	v_rcp_f32_e32 v16, v16
	v_rcp_f32_e32 v17, v17
	s_waitcnt vmcnt(19)
; __device__ __forceinline__ unsigned cvt_pk_bf16(float lo, float hi) { unsigned r; asm volatile("s_nop 0\n\tv_cvt_pk_bf16_f32 %0, %1, %2" : "=v"(r) : "v"(lo), "v"(hi)); return r; }
; #define PG8_BAR __builtin_amdgcn_s_barrier()
; template <class Epi, class Sched, bool ALIGN_EPI = false, bool SP2 = false, bool I8 = false>
; __device__ __forceinline__ void gemm_phase(PG8_LAS unsigned char* lds, const Gemm g, const Sched& S, const Epi& E) {
;     ...
;         if (!has_next) break;
; #pragma unroll
;         for (int a = 0; a < 2; ++a)
; #pragma unroll
;             for (int b = 0; b < 2; ++b)
; #pragma unroll
;                 for (int m = 0; m < 4; ++m)
; #pragma unroll
;                     for (int n = 0; n < 2; ++n) acc[a][b][m][n] = (typename AccT<I8>::type){0, 0, 0, 0};
;         cur = nxt; cA = nA; cB = nB; ++ui; nt = PG8_NT(cur);
;         if constexpr (ALIGN_EPI) { if (wr == 1) PG8_BAR; }
;     __device__ __forceinline__ void operator()(const typename AccT<I8>::type (&acc)[2][2][4][2], const Unit& u, int wr, int wc, int fr, int fq) const {
;     ...
;                     for (int n = 0; n < 2; ++n) { const size_t o = off + bj * HALF + n * 16; const f32x4 b = cur.b[bj][n]; f32x4 v;
;                         if constexpr (I8) v = __builtin_convertvector(acc[ai][bj][m][n], f32x4) * rs * sv[bj][n]; else v = acc[ai][bj][m][n];
;                         if (MODE == 1) { const u32x2 pw = cur.pw[bj][n]; const f32x4 pp = (f32x4){bf_lo(pw.x), bf_hi(pw.x), bf_lo(pw.y), bf_hi(pw.y)}; v = sig4(I8 ? v : v * rs) * pp; }
;                         const f32x4 x = b + v; *(f32x4*)(out + o) = x;
;                         if (MODE == 0 && XB) { u32x2 w; w.x = cvt_pk_bf16(x[0], x[1]); w.y = cvt_pk_bf16(x[2], x[3]); *(u32x2*)(XB + o) = w; ss += (x[0] * x[0] + x[1] * x[1]) + (x[2] * x[2] + x[3] * x[3]);
;                             if (RM) mx = fmaxf(fmaxf(mx, fmaxf(fabsf(x[0]), fabsf(x[1]))), fmaxf(fabsf(x[2]), fabsf(x[3]))); } }
;                 if (MODE == 0 && XB) { ss += __shfl_xor(ss, 16); ss += __shfl_xor(ss, 32); if (fq == 0) unsafeAtomicAdd(SS + r, ss);
;                     if (RM) { mx = fmaxf(mx, __shfl_xor(mx, 16)); mx = fmaxf(mx, __shfl_xor(mx, 32)); if (fq == 0) atomicMax(RM + r, __builtin_bit_cast(unsigned, mx)); } }
;                 cur = nxt; }
	v_lshlrev_b32_e32 v250, 16, v118
	v_and_b32_e32 v251, 0xffff0000, v118
	v_lshlrev_b32_e32 v252, 16, v119
	v_and_b32_e32 v253, 0xffff0000, v119
	v_pk_fma_f32 v[110:111], v[14:15], v[250:251], v[110:111]
	v_pk_fma_f32 v[112:113], v[16:17], v[252:253], v[112:113]
	global_store_dwordx4 v194, v[110:113], s[54:55] offset:0
	v_pk_mul_f32 v[10:11], v[248:249], v[10:11] op_sel:[1,0] op_sel_hi:[1,1]
	v_pk_mul_f32 v[12:13], v[248:249], v[12:13] op_sel:[1,0] op_sel_hi:[1,1]
	v_pk_mul_f32 v[10:11], v[66:67], v[10:11]
	v_pk_mul_f32 v[12:13], v[68:69], v[12:13]
	v_mul_f32_e32 v10, v255, v10
	v_mul_f32_e32 v11, v255, v11
	v_mul_f32_e32 v12, v255, v12
	v_mul_f32_e32 v13, v255, v13
	v_exp_f32_e32 v10, v10
	v_exp_f32_e32 v11, v11
	v_exp_f32_e32 v12, v12
	v_exp_f32_e32 v13, v13
	v_add_f32_e32 v10, 1.0, v10
	v_add_f32_e32 v11, 1.0, v11
	v_add_f32_e32 v12, 1.0, v12
	v_add_f32_e32 v13, 1.0, v13
	v_rcp_f32_e32 v10, v10
	v_rcp_f32_e32 v11, v11
	v_rcp_f32_e32 v12, v12
	v_rcp_f32_e32 v13, v13
	s_waitcnt vmcnt(19)
	v_lshlrev_b32_e32 v250, 16, v120
	v_and_b32_e32 v251, 0xffff0000, v120
	v_lshlrev_b32_e32 v252, 16, v121
	v_and_b32_e32 v253, 0xffff0000, v121
	v_pk_fma_f32 v[106:107], v[10:11], v[250:251], v[106:107]
	v_pk_fma_f32 v[108:109], v[12:13], v[252:253], v[108:109]
	global_store_dwordx4 v194, v[106:109], s[54:55] offset:64
	v_pk_mul_f32 v[6:7], v[248:249], v[6:7] op_sel:[1,0] op_sel_hi:[1,1]
	v_pk_mul_f32 v[8:9], v[248:249], v[8:9] op_sel:[1,0] op_sel_hi:[1,1]
	v_pk_mul_f32 v[6:7], v[74:75], v[6:7]
	v_pk_mul_f32 v[8:9], v[76:77], v[8:9]
	v_mul_f32_e32 v6, v255, v6
	v_mul_f32_e32 v7, v255, v7
	v_mul_f32_e32 v8, v255, v8
	v_mul_f32_e32 v9, v255, v9
	v_exp_f32_e32 v6, v6
	v_exp_f32_e32 v7, v7
	v_exp_f32_e32 v8, v8
	v_exp_f32_e32 v9, v9
	v_add_f32_e32 v6, 1.0, v6
	v_add_f32_e32 v7, 1.0, v7
	v_add_f32_e32 v8, 1.0, v8
	v_add_f32_e32 v9, 1.0, v9
	v_rcp_f32_e32 v6, v6
	v_rcp_f32_e32 v7, v7
	v_rcp_f32_e32 v8, v8
	v_rcp_f32_e32 v9, v9
	s_waitcnt vmcnt(19)
	v_lshlrev_b32_e32 v250, 16, v114
	v_and_b32_e32 v251, 0xffff0000, v114
	v_lshlrev_b32_e32 v252, 16, v115
	v_and_b32_e32 v253, 0xffff0000, v115
	v_pk_fma_f32 v[102:103], v[6:7], v[250:251], v[102:103]
	v_pk_fma_f32 v[104:105], v[8:9], v[252:253], v[104:105]
	global_store_dwordx4 v194, v[102:105], s[54:55] offset:512
	v_pk_mul_f32 v[2:3], v[248:249], v[2:3] op_sel:[1,0] op_sel_hi:[1,1]
	v_pk_mul_f32 v[4:5], v[248:249], v[4:5] op_sel:[1,0] op_sel_hi:[1,1]
	v_pk_mul_f32 v[2:3], v[78:79], v[2:3]
	v_pk_mul_f32 v[4:5], v[80:81], v[4:5]
	v_mul_f32_e32 v2, v255, v2
	v_mul_f32_e32 v3, v255, v3
	v_mul_f32_e32 v4, v255, v4
	v_mul_f32_e32 v5, v255, v5
	v_exp_f32_e32 v2, v2
	v_exp_f32_e32 v3, v3
	v_exp_f32_e32 v4, v4
	v_exp_f32_e32 v5, v5
	v_add_f32_e32 v2, 1.0, v2
	v_add_f32_e32 v3, 1.0, v3
	v_add_f32_e32 v4, 1.0, v4
	v_add_f32_e32 v5, 1.0, v5
	v_rcp_f32_e32 v2, v2
	v_rcp_f32_e32 v3, v3
	v_rcp_f32_e32 v4, v4
	v_rcp_f32_e32 v5, v5
	s_waitcnt vmcnt(19)
	v_lshlrev_b32_e32 v250, 16, v116
	v_and_b32_e32 v251, 0xffff0000, v116
	v_lshlrev_b32_e32 v252, 16, v117
	v_and_b32_e32 v253, 0xffff0000, v117
	v_pk_fma_f32 v[98:99], v[2:3], v[250:251], v[98:99]
	v_pk_fma_f32 v[100:101], v[4:5], v[252:253], v[100:101]
	global_store_dwordx4 v194, v[98:101], s[54:55] offset:576
	v_readlane_b32 s48, v254, 8
	s_mov_b64 s[26:27], s[54:55]
	s_andn2_b64 vcc, exec, s[0:1]
	s_mov_b64 s[0:1], -1
	v_readlane_b32 s49, v254, 9
	v_readlane_b32 s50, v254, 10
	v_readlane_b32 s51, v254, 11
	v_readlane_b32 s52, v254, 12
	v_readlane_b32 s53, v254, 13
	s_cbranch_vccnz .LBB0_2314
	s_andn2_b64 vcc, exec, s[4:5]
	s_cbranch_vccnz .LBB0_2313
	s_barrier
	s_branch .LBB0_2313
